# same as previous plus the 2 wait states between the ALiBi bias table build and the first MFMA that reads it as C
# baseline (speedup 1.0000x reference)
.LBB0_390:
	s_and_b64 vcc, exec, s[16:17]
	s_cbranch_vccz .LBB0_407
	s_waitcnt vmcnt(0)
	s_mov_b32 s98, 0x3e8293ee
	v_cvt_f32_i32_e32 v205, v189
	v_mul_f32_e32 v206, 0x407af232, v200
	v_mov_b32_e32 v114, 0
	v_mul_f32_e32 v115, 0x3f800000, v206
	v_mul_f32_e32 v116, 0x40000000, v206
	v_mul_f32_e32 v117, 0x40400000, v206
	v_mul_f32_e32 v118, 0x41000000, v206
	v_mul_f32_e32 v119, 0x41100000, v206
	v_mul_f32_e32 v120, 0x41200000, v206
	v_mul_f32_e32 v121, 0x41300000, v206
	v_mul_f32_e32 v122, 0x41800000, v206
	v_mul_f32_e32 v123, 0x41880000, v206
	v_mul_f32_e32 v124, 0x41900000, v206
	v_mul_f32_e32 v125, 0x41980000, v206
	v_mul_f32_e32 v126, 0x41c00000, v206
	v_mul_f32_e32 v127, 0x41c80000, v206
	v_mul_f32_e32 v128, 0x41d00000, v206
	v_mul_f32_e32 v129, 0x41d80000, v206
	s_nop 1
